# loop-edge hoist applied to the owners' up-projection K-loop as well (pointer increments and exit compare in the MFMA shadow)
# speedup vs baseline: 1.0023x; 1.0023x over previous
.LBB0_1876:
	v_add_u32_e32 v2, s83, v144
	ds_read_b128 v[146:149], v2
	ds_read_b128 v[150:153], v2 offset:1024
	ds_read_b128 v[154:157], v2 offset:2048
	ds_read_b128 v[158:161], v2 offset:3072
	v_add_u32_e32 v2, s44, v144
	ds_read_b128 v[162:165], v2
	ds_read_b128 v[166:169], v2 offset:1024
	ds_read_b128 v[170:173], v2 offset:2048
	ds_read_b128 v[174:177], v2 offset:3072
	s_add_i32 s70, s18, 2
	s_add_u32 s71, s42, 0x80
	s_addc_u32 s19, s43, 0
	s_cmp_eq_u32 s57, s18
	s_cselect_b32 s18, s34, s71
	s_cselect_b32 s19, s35, s19
	s_cselect_b32 s77, s25, s69
	s_cselect_b32 s76, s24, s68
	v_lshl_add_u64 v[210:211], s[42:43], 0, v[140:141]
	s_add_i32 m0, s23, 0xc000
	ds_read_b128 v[178:181], v145
	ds_read_b128 v[182:185], v145 offset:1024
	ds_read_b128 v[186:189], v145 offset:2048
	ds_read_b128 v[190:193], v145 offset:3072
	ds_read_b128 v[194:197], v145 offset:4096
	ds_read_b128 v[198:201], v145 offset:5120
	ds_read_b128 v[202:205], v145 offset:6144
	ds_read_b128 v[206:209], v145 offset:7168
	global_load_lds_dwordx4 v[210:211], off
	v_lshl_add_u64 v[210:211], s[42:43], 0, v[142:143]
	s_add_i32 m0, s23, 0xe000
	s_nop 0
	global_load_lds_dwordx4 v[210:211], off
	s_setprio 1
	s_waitcnt vmcnt(8)
	s_waitcnt lgkmcnt(0)
	s_barrier
	v_mfma_f32_16x16x32_bf16 v[120:123], v[146:149], v[178:181], v[120:123]
	v_mfma_f32_16x16x32_bf16 v[120:123], v[150:153], v[182:185], v[120:123]
	v_mfma_f32_16x16x32_bf16 v[112:115], v[146:149], v[186:189], v[112:115]
	v_mfma_f32_16x16x32_bf16 v[112:115], v[150:153], v[190:193], v[112:115]
	v_mfma_f32_16x16x32_bf16 v[96:99], v[146:149], v[194:197], v[96:99]
	v_mfma_f32_16x16x32_bf16 v[96:99], v[150:153], v[198:201], v[96:99]
	v_mfma_f32_16x16x32_bf16 v[80:83], v[146:149], v[202:205], v[80:83]
	v_mfma_f32_16x16x32_bf16 v[80:83], v[150:153], v[206:209], v[80:83]
	v_mfma_f32_16x16x32_bf16 v[76:79], v[154:157], v[202:205], v[76:79]
	v_mfma_f32_16x16x32_bf16 v[76:79], v[158:161], v[206:209], v[76:79]
	v_mfma_f32_16x16x32_bf16 v[92:95], v[154:157], v[194:197], v[92:95]
	v_mfma_f32_16x16x32_bf16 v[92:95], v[158:161], v[198:201], v[92:95]
	v_mfma_f32_16x16x32_bf16 v[108:111], v[154:157], v[186:189], v[108:111]
	v_mfma_f32_16x16x32_bf16 v[108:111], v[158:161], v[190:193], v[108:111]
	v_mfma_f32_16x16x32_bf16 v[128:131], v[154:157], v[178:181], v[128:131]
	v_mfma_f32_16x16x32_bf16 v[128:131], v[158:161], v[182:185], v[128:131]
	s_setprio 0
	s_setprio 1
	v_mfma_f32_16x16x32_bf16 v[124:127], v[162:165], v[178:181], v[124:127]
	v_mfma_f32_16x16x32_bf16 v[124:127], v[166:169], v[182:185], v[124:127]
	v_mfma_f32_16x16x32_bf16 v[104:107], v[162:165], v[186:189], v[104:107]
	v_mfma_f32_16x16x32_bf16 v[104:107], v[166:169], v[190:193], v[104:107]
	v_mfma_f32_16x16x32_bf16 v[88:91], v[162:165], v[194:197], v[88:91]
	v_mfma_f32_16x16x32_bf16 v[88:91], v[166:169], v[198:201], v[88:91]
	v_mfma_f32_16x16x32_bf16 v[72:75], v[162:165], v[202:205], v[72:75]
	v_mfma_f32_16x16x32_bf16 v[72:75], v[166:169], v[206:209], v[72:75]
	v_mfma_f32_16x16x32_bf16 v[68:71], v[170:173], v[202:205], v[68:71]
	v_mfma_f32_16x16x32_bf16 v[68:71], v[174:177], v[206:209], v[68:71]
	v_mfma_f32_16x16x32_bf16 v[84:87], v[170:173], v[194:197], v[84:87]
	v_mfma_f32_16x16x32_bf16 v[84:87], v[174:177], v[198:201], v[84:87]
	v_mfma_f32_16x16x32_bf16 v[100:103], v[170:173], v[186:189], v[100:103]
	v_mfma_f32_16x16x32_bf16 v[100:103], v[174:177], v[190:193], v[100:103]
	v_mfma_f32_16x16x32_bf16 v[116:119], v[170:173], v[178:181], v[116:119]
	v_mfma_f32_16x16x32_bf16 v[116:119], v[174:177], v[182:185], v[116:119]
	s_barrier
	s_setprio 0
	s_mov_b32 m0, s16
	v_lshl_add_u64 v[210:211], s[76:77], 0, v[134:135]
	v_lshl_add_u64 v[216:217], s[76:77], 0, v[138:139]
	s_add_u32 s76, s76, s4
	ds_read_b128 v[178:181], v145 offset:16384
	ds_read_b128 v[182:185], v145 offset:17408
	ds_read_b128 v[186:189], v145 offset:18432
	ds_read_b128 v[190:193], v145 offset:19456
	ds_read_b128 v[194:197], v145 offset:20480
	ds_read_b128 v[198:201], v145 offset:21504
	ds_read_b128 v[202:205], v145 offset:22528
	ds_read_b128 v[206:209], v145 offset:23552
	global_load_lds_dwordx4 v[210:211], off
	s_mov_b32 m0, s20
	s_addc_u32 s77, s77, s5
	global_load_lds_dwordx4 v[216:217], off
	v_lshl_add_u64 v[218:219], s[76:77], 0, v[134:135]
	s_mov_b32 m0, s21
	v_lshl_add_u64 v[220:221], s[76:77], 0, v[138:139]
	global_load_lds_dwordx4 v[218:219], off
	s_mov_b32 m0, s22
	v_lshl_add_u64 v[222:223], s[18:19], 0, v[132:133]
	global_load_lds_dwordx4 v[220:221], off
	s_mov_b32 m0, s23
	v_lshl_add_u64 v[224:225], s[18:19], 0, v[136:137]
	global_load_lds_dwordx4 v[222:223], off
	s_mov_b32 m0, s26
	s_nop 0
	global_load_lds_dwordx4 v[224:225], off
	s_setprio 1
	s_waitcnt vmcnt(8)
	s_waitcnt lgkmcnt(0)
	s_barrier
	v_mfma_f32_16x16x32_bf16 v[64:67], v[146:149], v[178:181], v[64:67]
	v_mfma_f32_16x16x32_bf16 v[64:67], v[150:153], v[182:185], v[64:67]
	v_mfma_f32_16x16x32_bf16 v[48:51], v[146:149], v[186:189], v[48:51]
	v_mfma_f32_16x16x32_bf16 v[48:51], v[150:153], v[190:193], v[48:51]
	v_mfma_f32_16x16x32_bf16 v[32:35], v[146:149], v[194:197], v[32:35]
	v_mfma_f32_16x16x32_bf16 v[32:35], v[150:153], v[198:201], v[32:35]
	v_mfma_f32_16x16x32_bf16 v[16:19], v[146:149], v[202:205], v[16:19]
	v_mfma_f32_16x16x32_bf16 v[16:19], v[150:153], v[206:209], v[16:19]
	v_mfma_f32_16x16x32_bf16 v[12:15], v[154:157], v[202:205], v[12:15]
	v_mfma_f32_16x16x32_bf16 v[12:15], v[158:161], v[206:209], v[12:15]
	v_mfma_f32_16x16x32_bf16 v[28:31], v[154:157], v[194:197], v[28:31]
	v_mfma_f32_16x16x32_bf16 v[28:31], v[158:161], v[198:201], v[28:31]
	v_mfma_f32_16x16x32_bf16 v[44:47], v[154:157], v[186:189], v[44:47]
	v_mfma_f32_16x16x32_bf16 v[44:47], v[158:161], v[190:193], v[44:47]
	v_mfma_f32_16x16x32_bf16 v[60:63], v[154:157], v[178:181], v[60:63]
	v_mfma_f32_16x16x32_bf16 v[60:63], v[158:161], v[182:185], v[60:63]
	s_setprio 0
	s_setprio 1
	v_mfma_f32_16x16x32_bf16 v[56:59], v[162:165], v[178:181], v[56:59]
	v_mfma_f32_16x16x32_bf16 v[56:59], v[166:169], v[182:185], v[56:59]
	v_mfma_f32_16x16x32_bf16 v[40:43], v[162:165], v[186:189], v[40:43]
	v_mfma_f32_16x16x32_bf16 v[40:43], v[166:169], v[190:193], v[40:43]
	v_mfma_f32_16x16x32_bf16 v[24:27], v[162:165], v[194:197], v[24:27]
	v_mfma_f32_16x16x32_bf16 v[24:27], v[166:169], v[198:201], v[24:27]
	v_mfma_f32_16x16x32_bf16 v[8:11], v[162:165], v[202:205], v[8:11]
	v_mfma_f32_16x16x32_bf16 v[8:11], v[166:169], v[206:209], v[8:11]
	v_mfma_f32_16x16x32_bf16 v[4:7], v[170:173], v[202:205], v[4:7]
	v_mfma_f32_16x16x32_bf16 v[4:7], v[174:177], v[206:209], v[4:7]
	v_mfma_f32_16x16x32_bf16 v[20:23], v[170:173], v[194:197], v[20:23]
	v_mfma_f32_16x16x32_bf16 v[20:23], v[174:177], v[198:201], v[20:23]
	v_mfma_f32_16x16x32_bf16 v[36:39], v[170:173], v[186:189], v[36:39]
	v_mfma_f32_16x16x32_bf16 v[36:39], v[174:177], v[190:193], v[36:39]
	v_mfma_f32_16x16x32_bf16 v[52:55], v[170:173], v[178:181], v[52:55]
	v_mfma_f32_16x16x32_bf16 v[52:55], v[174:177], v[182:185], v[52:55]
	s_barrier
	s_setprio 0
	v_add_u32_e32 v2, s45, v144
	ds_read_b128 v[146:149], v2
	ds_read_b128 v[150:153], v2 offset:1024
	ds_read_b128 v[154:157], v2 offset:2048
	ds_read_b128 v[158:161], v2 offset:3072
	v_add_u32_e32 v2, s74, v144
	ds_read_b128 v[162:165], v2
	ds_read_b128 v[166:169], v2 offset:1024
	ds_read_b128 v[170:173], v2 offset:2048
	ds_read_b128 v[174:177], v2 offset:3072
	s_add_u32 s18, s18, s4
	s_addc_u32 s19, s19, s5
	s_mov_b32 m0, s27
	v_lshl_add_u64 v[226:227], s[18:19], 0, v[132:133]
	ds_read_b128 v[178:181], v145 offset:32768
	ds_read_b128 v[182:185], v145 offset:33792
	ds_read_b128 v[186:189], v145 offset:34816
	ds_read_b128 v[190:193], v145 offset:35840
	ds_read_b128 v[194:197], v145 offset:36864
	ds_read_b128 v[198:201], v145 offset:37888
	ds_read_b128 v[202:205], v145 offset:38912
	ds_read_b128 v[206:209], v145 offset:39936
	global_load_lds_dwordx4 v[226:227], off
	v_lshl_add_u64 v[226:227], s[18:19], 0, v[136:137]
	s_mov_b32 m0, s37
	s_nop 0
	global_load_lds_dwordx4 v[226:227], off
	s_setprio 1
	s_waitcnt vmcnt(8)
	s_waitcnt lgkmcnt(0)
	s_barrier
	v_mfma_f32_16x16x32_bf16 v[120:123], v[146:149], v[178:181], v[120:123]
	v_mfma_f32_16x16x32_bf16 v[120:123], v[150:153], v[182:185], v[120:123]
	v_mfma_f32_16x16x32_bf16 v[112:115], v[146:149], v[186:189], v[112:115]
	v_mfma_f32_16x16x32_bf16 v[112:115], v[150:153], v[190:193], v[112:115]
	v_mfma_f32_16x16x32_bf16 v[96:99], v[146:149], v[194:197], v[96:99]
	v_mfma_f32_16x16x32_bf16 v[96:99], v[150:153], v[198:201], v[96:99]
	v_mfma_f32_16x16x32_bf16 v[80:83], v[146:149], v[202:205], v[80:83]
	v_mfma_f32_16x16x32_bf16 v[80:83], v[150:153], v[206:209], v[80:83]
	v_mfma_f32_16x16x32_bf16 v[76:79], v[154:157], v[202:205], v[76:79]
	v_mfma_f32_16x16x32_bf16 v[76:79], v[158:161], v[206:209], v[76:79]
	v_mfma_f32_16x16x32_bf16 v[92:95], v[154:157], v[194:197], v[92:95]
	v_mfma_f32_16x16x32_bf16 v[92:95], v[158:161], v[198:201], v[92:95]
	v_mfma_f32_16x16x32_bf16 v[108:111], v[154:157], v[186:189], v[108:111]
	v_mfma_f32_16x16x32_bf16 v[108:111], v[158:161], v[190:193], v[108:111]
	v_mfma_f32_16x16x32_bf16 v[128:131], v[154:157], v[178:181], v[128:131]
	v_mfma_f32_16x16x32_bf16 v[128:131], v[158:161], v[182:185], v[128:131]
	s_setprio 0
	s_setprio 1
	v_mfma_f32_16x16x32_bf16 v[124:127], v[162:165], v[178:181], v[124:127]
	v_mfma_f32_16x16x32_bf16 v[124:127], v[166:169], v[182:185], v[124:127]
	v_mfma_f32_16x16x32_bf16 v[104:107], v[162:165], v[186:189], v[104:107]
	v_mfma_f32_16x16x32_bf16 v[104:107], v[166:169], v[190:193], v[104:107]
	v_mfma_f32_16x16x32_bf16 v[88:91], v[162:165], v[194:197], v[88:91]
	v_mfma_f32_16x16x32_bf16 v[88:91], v[166:169], v[198:201], v[88:91]
	v_mfma_f32_16x16x32_bf16 v[72:75], v[162:165], v[202:205], v[72:75]
	v_mfma_f32_16x16x32_bf16 v[72:75], v[166:169], v[206:209], v[72:75]
	v_mfma_f32_16x16x32_bf16 v[68:71], v[170:173], v[202:205], v[68:71]
	v_mfma_f32_16x16x32_bf16 v[68:71], v[174:177], v[206:209], v[68:71]
	v_mfma_f32_16x16x32_bf16 v[84:87], v[170:173], v[194:197], v[84:87]
	v_mfma_f32_16x16x32_bf16 v[84:87], v[174:177], v[198:201], v[84:87]
	v_mfma_f32_16x16x32_bf16 v[100:103], v[170:173], v[186:189], v[100:103]
	v_mfma_f32_16x16x32_bf16 v[100:103], v[174:177], v[190:193], v[100:103]
	v_mfma_f32_16x16x32_bf16 v[116:119], v[170:173], v[178:181], v[116:119]
	v_mfma_f32_16x16x32_bf16 v[116:119], v[174:177], v[182:185], v[116:119]
	s_barrier
	s_setprio 0
	s_mov_b32 m0, s49
	v_lshl_add_u64 v[210:211], v[210:211], 0, s[64:65]
	ds_read_b128 v[178:181], v145 offset:49152
	ds_read_b128 v[182:185], v145 offset:50176
	ds_read_b128 v[186:189], v145 offset:51200
	ds_read_b128 v[190:193], v145 offset:52224
	ds_read_b128 v[194:197], v145 offset:53248
	ds_read_b128 v[198:201], v145 offset:54272
	ds_read_b128 v[202:205], v145 offset:55296
	ds_read_b128 v[206:209], v145 offset:56320
	global_load_lds_dwordx4 v[210:211], off
	v_lshl_add_u64 v[210:211], v[216:217], 0, s[64:65]
	s_mov_b32 m0, s50
	s_nop 0
	global_load_lds_dwordx4 v[210:211], off
	v_lshl_add_u64 v[210:211], v[218:219], 0, s[64:65]
	s_mov_b32 m0, s53
	s_nop 0
	global_load_lds_dwordx4 v[210:211], off
	v_lshl_add_u64 v[210:211], v[220:221], 0, s[64:65]
	s_mov_b32 m0, s56
	s_nop 0
	global_load_lds_dwordx4 v[210:211], off
	v_lshl_add_u64 v[210:211], v[222:223], 0, s[64:65]
	s_mov_b32 m0, s51
	s_nop 0
	global_load_lds_dwordx4 v[210:211], off
	v_lshl_add_u64 v[210:211], v[224:225], 0, s[64:65]
	s_mov_b32 m0, s52
	s_nop 0
	global_load_lds_dwordx4 v[210:211], off
	s_setprio 1
	s_waitcnt vmcnt(8)
	s_waitcnt lgkmcnt(0)
	s_barrier
	v_mfma_f32_16x16x32_bf16 v[64:67], v[146:149], v[178:181], v[64:67]
	v_mfma_f32_16x16x32_bf16 v[64:67], v[150:153], v[182:185], v[64:67]
	v_mfma_f32_16x16x32_bf16 v[48:51], v[146:149], v[186:189], v[48:51]
	v_mfma_f32_16x16x32_bf16 v[48:51], v[150:153], v[190:193], v[48:51]
	v_mfma_f32_16x16x32_bf16 v[32:35], v[146:149], v[194:197], v[32:35]
	v_mfma_f32_16x16x32_bf16 v[32:35], v[150:153], v[198:201], v[32:35]
	v_mfma_f32_16x16x32_bf16 v[16:19], v[146:149], v[202:205], v[16:19]
	v_mfma_f32_16x16x32_bf16 v[16:19], v[150:153], v[206:209], v[16:19]
	v_mfma_f32_16x16x32_bf16 v[12:15], v[154:157], v[202:205], v[12:15]
	v_mfma_f32_16x16x32_bf16 v[12:15], v[158:161], v[206:209], v[12:15]
	v_mfma_f32_16x16x32_bf16 v[28:31], v[154:157], v[194:197], v[28:31]
	v_mfma_f32_16x16x32_bf16 v[28:31], v[158:161], v[198:201], v[28:31]
	v_mfma_f32_16x16x32_bf16 v[44:47], v[154:157], v[186:189], v[44:47]
	v_mfma_f32_16x16x32_bf16 v[44:47], v[158:161], v[190:193], v[44:47]
	v_mfma_f32_16x16x32_bf16 v[60:63], v[154:157], v[178:181], v[60:63]
	v_mfma_f32_16x16x32_bf16 v[60:63], v[158:161], v[182:185], v[60:63]
	s_setprio 0
	s_setprio 1
	v_mfma_f32_16x16x32_bf16 v[56:59], v[162:165], v[178:181], v[56:59]
	v_mfma_f32_16x16x32_bf16 v[56:59], v[166:169], v[182:185], v[56:59]
	v_mfma_f32_16x16x32_bf16 v[40:43], v[162:165], v[186:189], v[40:43]
	v_mfma_f32_16x16x32_bf16 v[40:43], v[166:169], v[190:193], v[40:43]
	v_mfma_f32_16x16x32_bf16 v[24:27], v[162:165], v[194:197], v[24:27]
	v_mfma_f32_16x16x32_bf16 v[24:27], v[166:169], v[198:201], v[24:27]
	v_mfma_f32_16x16x32_bf16 v[8:11], v[162:165], v[202:205], v[8:11]
	v_mfma_f32_16x16x32_bf16 v[8:11], v[166:169], v[206:209], v[8:11]
	s_add_u32 s42, s42, 0x100
	s_addc_u32 s43, s43, 0
	v_mfma_f32_16x16x32_bf16 v[4:7], v[170:173], v[202:205], v[4:7]
	v_mfma_f32_16x16x32_bf16 v[4:7], v[174:177], v[206:209], v[4:7]
	s_add_u32 s68, s68, 0x100
	s_addc_u32 s69, s69, 0
	v_mfma_f32_16x16x32_bf16 v[20:23], v[170:173], v[194:197], v[20:23]
	v_mfma_f32_16x16x32_bf16 v[20:23], v[174:177], v[198:201], v[20:23]
	s_cmp_ge_i32 s70, s46
	v_mfma_f32_16x16x32_bf16 v[36:39], v[170:173], v[186:189], v[36:39]
	v_mfma_f32_16x16x32_bf16 v[36:39], v[174:177], v[190:193], v[36:39]
	v_mfma_f32_16x16x32_bf16 v[52:55], v[170:173], v[178:181], v[52:55]
	v_mfma_f32_16x16x32_bf16 v[52:55], v[174:177], v[182:185], v[52:55]
	s_barrier
	s_setprio 0
	s_mov_b32 s18, s70
	s_cbranch_scc0 .LBB0_1876
